# prep phase: p->bf16 conversion loop issues 4 loads per round trip instead of 1 (was load/wait/store serialised)
# speedup vs baseline: 1.0020x; 1.0020x over previous
; __device__ __forceinline__ void st_bf4(bfraw* p, f32x4 v) { u32x2 o; o[0] = pack2(v[0], v[1]); o[1] = pack2(v[2], v[3]); *(u32x2*)p = o; }
; __device__ __forceinline__ void phase_prep(CPR P) {
;     ...
;     const float* p = P.in[1]; bfraw* pb = (bfraw*)(P.ws + WS_PB);
;     const size_t n4 = (size_t)2 * S * PLE / 4;
;     for (size_t i = (size_t)blockIdx.x * NTHREADS + tid; i < n4; i += (size_t)gridDim.x * NTHREADS) st_bf4(pb + i * 4, __builtin_nontemporal_load((const f32x4*)(p + i * 4)));
.Lpb_batch:
	v_readfirstlane_b32 s98, v2
	s_lshl_b32 s99, s6, 1
	s_add_u32 s99, s99, s6
	s_add_u32 s98, s98, s99
	s_cmp_gt_u32 s98, s14
	s_cbranch_scc1 .LBB0_375
	global_load_dwordx4 v[8:11], v[4:5], off nt
	v_lshl_add_u64 v[4:5], v[4:5], 0, s[8:9]
	global_load_dwordx4 v[12:15], v[4:5], off nt
	v_lshl_add_u64 v[4:5], v[4:5], 0, s[8:9]
	global_load_dwordx4 v[16:19], v[4:5], off nt
	v_lshl_add_u64 v[4:5], v[4:5], 0, s[8:9]
	global_load_dwordx4 v[20:23], v[4:5], off nt
	v_lshl_add_u64 v[4:5], v[4:5], 0, s[8:9]
	v_lshl_add_u64 v[2:3], v[2:3], 0, s[6:7]
	v_lshl_add_u64 v[2:3], v[2:3], 0, s[6:7]
	v_lshl_add_u64 v[2:3], v[2:3], 0, s[6:7]
	v_lshl_add_u64 v[2:3], v[2:3], 0, s[6:7]
	s_waitcnt vmcnt(0)
	v_cvt_pk_bf16_f32 v8, v8, v9
	v_cvt_pk_bf16_f32 v9, v10, v11
	global_store_dwordx2 v[6:7], v[8:9], off
	v_lshl_add_u64 v[6:7], v[6:7], 0, s[10:11]
	v_cvt_pk_bf16_f32 v12, v12, v13
	v_cvt_pk_bf16_f32 v13, v14, v15
	global_store_dwordx2 v[6:7], v[12:13], off
	v_lshl_add_u64 v[6:7], v[6:7], 0, s[10:11]
	v_cvt_pk_bf16_f32 v16, v16, v17
	v_cvt_pk_bf16_f32 v17, v18, v19
	global_store_dwordx2 v[6:7], v[16:17], off
	v_lshl_add_u64 v[6:7], v[6:7], 0, s[10:11]
	v_cvt_pk_bf16_f32 v20, v20, v21
	v_cvt_pk_bf16_f32 v21, v22, v23
	global_store_dwordx2 v[6:7], v[20:21], off
	v_lshl_add_u64 v[6:7], v[6:7], 0, s[10:11]
	v_cmp_lt_u64_e32 vcc, s[14:15], v[2:3]
	s_cbranch_vccnz .LBB0_376
	s_branch .Lpb_batch
